# first grid barrier (after phase 0) also uses the XCD-hierarchical barrier: census completion wait replaces the cooperative-groups sync
# speedup vs baseline: 1.0248x; 1.0102x over previous
; DI int TID() { int t = threadIdx.x; asm volatile("" : "+v"(t)); return t; }
; DI void grid_barrier_light(unsigned* ctr, unsigned target) {
;   asm volatile("s_waitcnt vmcnt(0)" ::: "memory");
;   __syncthreads();
;   if (TID() == 0) {
;     __builtin_amdgcn_fence(__ATOMIC_RELEASE, "agent");
;     asm volatile("s_waitcnt vmcnt(0)" ::: "memory");
;     __hip_atomic_fetch_add(ctr, 1u, __ATOMIC_RELAXED, __HIP_MEMORY_SCOPE_AGENT);
;     while (__hip_atomic_load(ctr, __ATOMIC_RELAXED, __HIP_MEMORY_SCOPE_AGENT) < target) { }
;     __builtin_amdgcn_fence(__ATOMIC_ACQUIRE, "agent");
;     asm volatile("s_waitcnt vmcnt(0)" ::: "memory");
;   }
; __global__ void __launch_bounds__(256, 2) hybrid_megakernel(Params p) {
;   __shared__ __attribute__((aligned(16))) char smem[SMEM_BYTES];
;   unsigned epoch = 0;
;   for (int ph = p.ph_lo; ph < p.ph_hi; ++ph) {
.LBB0_1:
	s_getreg_b32 s100, hwreg(HW_REG_XCC_ID, 0, 4)
	s_load_dwordx2 s[4:5], s[0:1], 0x280
	s_load_dwordx2 s[6:7], s[0:1], 0x250
	s_mov_b32 s101, 0
	v_and_b32_e32 v1, 0x3ff, v0
	v_mov_b32_e32 v2, 0
	v_mov_b32_e32 v3, 1
	s_and_b32 s100, s100, 15
	s_lshl_b32 s10, s100, 2
	s_add_u32 s10, s10, 32
	v_mov_b32_e32 v4, s10
	s_waitcnt lgkmcnt(0)
	s_cmp_lg_u32 s2, 0
	s_cbranch_scc1 .Lxb_zero_done
	v_cmp_gt_u32_e32 vcc, 64, v1
	s_and_saveexec_b64 s[8:9], vcc
	s_cbranch_execz .Lxb_zero_skip
	v_lshlrev_b32_e32 v5, 8, v1
	global_store_dword v5, v2, s[6:7] sc0 sc1
	s_waitcnt vmcnt(0)

; __global__ void __launch_bounds__(256, 2) hybrid_megakernel(Params p) {
;   __shared__ __attribute__((aligned(16))) char smem[SMEM_BYTES];
;   unsigned epoch = 0;
;   for (int ph = p.ph_lo; ph < p.ph_hi; ++ph) {
.Lxb_zero_done:
	v_cmp_eq_u32_e32 vcc, 0, v1
	s_and_saveexec_b64 s[8:9], vcc
	s_cbranch_execz .Lxb_census_done
	global_atomic_add v4, v3, s[4:5]
.Lxb_census_done:
	s_or_b64 exec, exec, s[8:9]
	s_load_dwordx16 s[4:19], s[0:1], 0x0
	s_load_dwordx16 s[36:51], s[0:1], 0x40
	s_mov_b32 s88, s2
	s_cmpk_lt_i32 s88, 0x400
	v_and_b32_e32 v224, 0x3ff, v0
	v_and_b32_e32 v0, 0x3fffffff, v0
	s_waitcnt lgkmcnt(0)
	v_writelane_b32 v253, s36, 0
	v_mbcnt_lo_u32_b32 v226, -1, 0
	s_mov_b32 s97, 0
	v_writelane_b32 v253, s37, 1
	v_writelane_b32 v253, s38, 2
	v_writelane_b32 v253, s39, 3
	v_writelane_b32 v253, s40, 4
	v_writelane_b32 v253, s41, 5
	v_writelane_b32 v253, s42, 6
	v_writelane_b32 v253, s43, 7
	v_writelane_b32 v253, s44, 8
	v_writelane_b32 v253, s45, 9
	v_writelane_b32 v253, s46, 10
	v_writelane_b32 v253, s47, 11
	v_writelane_b32 v253, s48, 12
	v_writelane_b32 v253, s49, 13
	v_writelane_b32 v253, s50, 14
	v_writelane_b32 v253, s51, 15
	s_load_dwordx16 s[36:51], s[0:1], 0x80
	v_mov_b32_e32 v189, 0
	v_mov_b32_e32 v225, 0x358637bd
	v_mbcnt_hi_u32_b32 v227, -1, v226
	v_mov_b32_e32 v228, 0xff800000
	s_waitcnt lgkmcnt(0)
	v_writelane_b32 v253, s36, 16
	v_mov_b32_e32 v229, 0x41b17218
	v_mov_b32_e32 v230, 0x80
	v_writelane_b32 v253, s37, 17
	v_writelane_b32 v253, s38, 18
	v_writelane_b32 v253, s39, 19
	v_writelane_b32 v253, s40, 20
	v_writelane_b32 v253, s41, 21
	v_writelane_b32 v253, s42, 22
	v_writelane_b32 v253, s43, 23
	v_writelane_b32 v253, s44, 24
	v_writelane_b32 v253, s45, 25
	v_writelane_b32 v253, s46, 26
	v_writelane_b32 v253, s47, 27
	v_writelane_b32 v253, s48, 28
	v_writelane_b32 v253, s49, 29
	v_writelane_b32 v253, s50, 30
	v_writelane_b32 v253, s51, 31
	s_load_dwordx16 s[36:51], s[0:1], 0xc0
	v_mov_b32_e32 v231, 0x3f80
	v_mov_b32_e32 v236, 0x9f
	v_mov_b32_e32 v222, 0x8200
	s_waitcnt lgkmcnt(0)
	v_writelane_b32 v253, s36, 32
	s_nop 1
	v_writelane_b32 v253, s37, 33
	v_writelane_b32 v253, s38, 34
	v_writelane_b32 v253, s39, 35
	v_writelane_b32 v253, s40, 36
	v_writelane_b32 v253, s41, 37
	v_writelane_b32 v253, s42, 38
	v_writelane_b32 v253, s43, 39
	v_writelane_b32 v253, s44, 40
	v_writelane_b32 v253, s45, 41
	v_writelane_b32 v253, s46, 42
	v_writelane_b32 v253, s47, 43
	v_writelane_b32 v253, s48, 44
	v_writelane_b32 v253, s49, 45
	v_writelane_b32 v253, s50, 46
	v_writelane_b32 v253, s51, 47
	s_load_dwordx16 s[36:51], s[0:1], 0x100
	s_waitcnt lgkmcnt(0)
	v_writelane_b32 v253, s36, 48
	s_nop 1
	v_writelane_b32 v253, s37, 49
	v_writelane_b32 v253, s38, 50
	v_writelane_b32 v253, s39, 51
	v_writelane_b32 v253, s40, 52
	v_writelane_b32 v253, s41, 53
	v_writelane_b32 v253, s42, 54
	v_writelane_b32 v253, s43, 55
	v_writelane_b32 v253, s44, 56
	v_writelane_b32 v253, s45, 57
	v_writelane_b32 v253, s46, 58
	v_writelane_b32 v253, s47, 59
	v_writelane_b32 v253, s48, 60
	v_writelane_b32 v253, s49, 61
	v_writelane_b32 v253, s50, 62
	v_writelane_b32 v253, s51, 63
	s_load_dwordx16 s[36:51], s[0:1], 0x140
	s_load_dwordx2 s[2:3], s[0:1], 0x180
	s_load_dwordx16 s[68:83], s[0:1], 0x198
	s_load_dwordx16 s[52:67], s[0:1], 0x1d8
	s_load_dwordx4 s[20:23], s[0:1], 0x238
	s_load_dwordx8 s[24:31], s[0:1], 0x218
	s_waitcnt lgkmcnt(0)
	v_writelane_b32 v254, s2, 0
	s_nop 1
	v_writelane_b32 v254, s3, 1
	v_writelane_b32 v254, s52, 2
	s_load_dwordx2 s[2:3], s[0:1], 0x248
	s_nop 0
	v_writelane_b32 v254, s53, 3
	v_writelane_b32 v254, s54, 4
	v_writelane_b32 v254, s55, 5
	v_writelane_b32 v254, s56, 6
	v_writelane_b32 v254, s57, 7
	v_writelane_b32 v254, s58, 8
	v_writelane_b32 v254, s59, 9
	v_writelane_b32 v254, s60, 10
	v_writelane_b32 v254, s61, 11
	v_writelane_b32 v254, s62, 12
	v_writelane_b32 v254, s63, 13
	v_writelane_b32 v254, s64, 14
	v_writelane_b32 v254, s65, 15
	v_writelane_b32 v254, s66, 16
	v_writelane_b32 v254, s67, 17
	s_waitcnt lgkmcnt(0)
; __global__ void __launch_bounds__(256, 2) hybrid_megakernel(Params p) {
;   __shared__ __attribute__((aligned(16))) char smem[SMEM_BYTES];
;   unsigned epoch = 0;
;   for (int ph = p.ph_lo; ph < p.ph_hi; ++ph) {
;     const int L = ph / NPH, s = ph % NPH;
;     if (s == 0 && L > 0) continue;
	v_writelane_b32 v254, s2, 18
	s_nop 1
	v_writelane_b32 v254, s3, 19
	v_writelane_b32 v254, s24, 20
	s_load_dwordx2 s[2:3], s[0:1], 0x270
	s_nop 0
	v_writelane_b32 v254, s25, 21
	v_writelane_b32 v254, s26, 22
	v_writelane_b32 v254, s27, 23
	v_writelane_b32 v254, s28, 24
	v_writelane_b32 v254, s29, 25
	v_writelane_b32 v254, s30, 26
	v_writelane_b32 v254, s31, 27
	s_load_dwordx4 s[24:27], s[0:1], 0x260
	s_waitcnt lgkmcnt(0)
	v_writelane_b32 v254, s2, 28
	s_nop 1
	v_writelane_b32 v254, s3, 29
	s_load_dwordx2 s[2:3], s[0:1], 0x280
	v_writelane_b32 v254, s24, 30
	s_nop 1
	v_writelane_b32 v254, s25, 31
	v_writelane_b32 v254, s26, 32
	v_writelane_b32 v254, s27, 33
	s_waitcnt lgkmcnt(0)
	v_writelane_b32 v254, s2, 34
	s_nop 1
	v_writelane_b32 v254, s3, 35
	s_cselect_b64 s[2:3], -1, 0
	v_writelane_b32 v254, s2, 36
	s_add_u32 s0, s0, 0x288
	s_addc_u32 s1, s1, 0
	v_writelane_b32 v254, s3, 37
	v_writelane_b32 v254, s0, 38
	s_cmpk_lt_i32 s88, 0x784
	s_mov_b32 s2, 0
	v_writelane_b32 v254, s1, 39
	s_cselect_b64 s[0:1], -1, 0
	v_writelane_b32 v254, s0, 40
	s_cmp_lg_u64 s[16:17], 0
	s_nop 0
	v_writelane_b32 v254, s1, 41
	s_cselect_b64 s[0:1], -1, 0
	v_writelane_b32 v254, s0, 42
	s_cmp_lg_u64 s[14:15], 0
	s_nop 0
	v_writelane_b32 v254, s1, 43
	s_cselect_b64 s[0:1], -1, 0
	v_writelane_b32 v254, s0, 44
	s_nop 1
	v_writelane_b32 v254, s1, 45
	v_writelane_b32 v254, s4, 46
	s_cmp_lg_u64 s[10:11], 0
	s_cselect_b64 s[0:1], -1, 0
	v_writelane_b32 v254, s5, 47
	v_writelane_b32 v254, s6, 48
	v_writelane_b32 v254, s7, 49
	v_writelane_b32 v254, s8, 50
	v_writelane_b32 v254, s9, 51
	v_writelane_b32 v254, s10, 52
	v_writelane_b32 v254, s11, 53
	v_writelane_b32 v254, s12, 54
	v_writelane_b32 v254, s13, 55
	v_writelane_b32 v254, s14, 56
	v_writelane_b32 v254, s15, 57
	v_writelane_b32 v254, s16, 58
	v_writelane_b32 v254, s17, 59
	v_writelane_b32 v254, s18, 60
	v_writelane_b32 v254, s19, 61
	v_writelane_b32 v254, s0, 62
	s_cmpk_lt_i32 s88, 0x200
	v_readlane_b32 s4, v253, 32
	v_writelane_b32 v254, s1, 63
	s_cselect_b64 s[0:1], -1, 0
	v_writelane_b32 v255, s0, 0
	s_cmpk_lt_i32 s88, 0x800
	v_readlane_b32 s10, v253, 38
	v_writelane_b32 v255, s1, 1
	s_cselect_b64 s[0:1], -1, 0
	v_readlane_b32 s11, v253, 39
	v_writelane_b32 v255, s0, 2
	s_cmp_lg_u64 s[10:11], 0
	v_readlane_b32 s5, v253, 33
	v_writelane_b32 v255, s1, 3
	s_cselect_b64 s[0:1], -1, 0
	v_writelane_b32 v255, s0, 4
	s_cmp_lg_u64 s[4:5], 0
	s_mov_b32 s10, s84
	v_writelane_b32 v255, s1, 5
	s_cselect_b64 s[0:1], -1, 0
	v_writelane_b32 v255, s0, 6
	s_cmpk_lt_i32 s88, 0xd80
	v_readlane_b32 s13, v253, 41
	v_writelane_b32 v255, s1, 7
	s_cselect_b64 s[0:1], -1, 0
	v_writelane_b32 v255, s0, 8
	s_cmpk_lt_i32 s88, 0x3ac4
	s_movk_i32 s13, 0x84
	v_writelane_b32 v255, s1, 9
	s_cselect_b64 s[0:1], -1, 0
	v_writelane_b32 v255, s0, 10
	v_readlane_b32 s6, v253, 34
	v_readlane_b32 s7, v253, 35
	v_writelane_b32 v255, s1, 11
	v_cmp_eq_u32_e64 s[0:1], 0, v0
	v_readlane_b32 s8, v253, 36
	v_readlane_b32 s9, v253, 37
	v_writelane_b32 v255, s0, 12
	v_readlane_b32 s12, v253, 40
	v_readlane_b32 s14, v253, 42
	v_writelane_b32 v255, s1, 13
	s_add_u32 s0, s22, 0x80
	v_writelane_b32 v255, s20, 14
	s_addc_u32 s1, s23, 0
	v_readlane_b32 s15, v253, 43
	v_writelane_b32 v255, s21, 15
	v_writelane_b32 v255, s22, 16
	v_writelane_b32 v255, s23, 17
	v_writelane_b32 v255, s0, 18
	v_readlane_b32 s16, v253, 44
	v_readlane_b32 s17, v253, 45
	v_writelane_b32 v255, s1, 19
	s_add_u32 s0, s80, 0x80
	v_writelane_b32 v255, s0, 20
	s_addc_u32 s0, s81, 0
	v_writelane_b32 v255, s0, 21
	v_writelane_b32 v255, s2, 22
	v_writelane_b32 v255, s84, 23
	s_mov_b32 s0, 0x5040100
	s_movk_i32 s1, 0x1580
	v_writelane_b32 v255, s85, 24
	v_writelane_b32 v255, s88, 25
	v_readlane_b32 s18, v253, 46
	v_readlane_b32 s19, v253, 47
	s_branch .LBB0_3

; DI int TID() { int t = threadIdx.x; asm volatile("" : "+v"(t)); return t; }
; DI void grid_barrier() { cg::this_grid().sync(); }
; DI void grid_barrier_light(unsigned* ctr, unsigned target) {
;   asm volatile("s_waitcnt vmcnt(0)" ::: "memory");
;   __syncthreads();
;   if (TID() == 0) {
;     __builtin_amdgcn_fence(__ATOMIC_RELEASE, "agent");
;     asm volatile("s_waitcnt vmcnt(0)" ::: "memory");
;     __hip_atomic_fetch_add(ctr, 1u, __ATOMIC_RELAXED, __HIP_MEMORY_SCOPE_AGENT);
;     while (__hip_atomic_load(ctr, __ATOMIC_RELAXED, __HIP_MEMORY_SCOPE_AGENT) < target) { }
;     __builtin_amdgcn_fence(__ATOMIC_ACQUIRE, "agent");
;     asm volatile("s_waitcnt vmcnt(0)" ::: "memory");
;   }
; __global__ void __launch_bounds__(256, 2) hybrid_megakernel(Params p) {
;     ...
;     if (ph + 1 < p.ph_hi) {
;       if (ph == p.ph_lo) grid_barrier();
;       else { ++epoch; grid_barrier_light(p.bar, epoch * gridDim.x); }
;     }
.LBB0_2017:
	v_readlane_b32 s2, v255, 30
	s_add_i32 s10, s2, 1
	s_cmp_ge_i32 s10, s85
	v_readlane_b32 s8, v255, 22
	s_cbranch_scc1 .LBB0_2038
	s_cmp_lg_u32 s84, s85
	s_mov_b64 s[2:3], -1
	s_cbranch_scc0 .LBB0_2026
	s_waitcnt vmcnt(0)
	v_readlane_b32 s2, v255, 22
	v_mov_b32_e32 v0, v224
	s_add_i32 s8, s2, 1
	s_waitcnt vmcnt(63) expcnt(7) lgkmcnt(15)
	s_barrier
	s_nop 0
	v_cmp_eq_u32_e32 vcc, 0, v0
	s_and_saveexec_b64 s[2:3], vcc
	s_cbranch_execz .LBB0_2025
	v_readlane_b32 s4, v254, 38
	v_readlane_b32 s5, v254, 39
	s_nop 3
	s_load_dword s9, s[4:5], 0x0
	s_sub_u32 s4, s4, 0x288
	s_subb_u32 s5, s5, 0
	s_load_dwordx2 s[6:7], s[4:5], 0x250
	s_lshr_b32 s14, s100, 8
	s_cmp_lg_u32 s14, 0
	s_cbranch_scc1 .Lxb_ready
	s_load_dwordx2 s[4:5], s[4:5], 0x280
	v_mov_b32_e32 v1, 0
	s_mov_b32 s101, 0
	s_waitcnt lgkmcnt(0)
.Lxb_census_retry:
	global_load_dword v4, v1, s[4:5] offset:32 sc1
	global_load_dword v5, v1, s[4:5] offset:36 sc1
	global_load_dword v6, v1, s[4:5] offset:40 sc1
	global_load_dword v7, v1, s[4:5] offset:44 sc1
	global_load_dword v8, v1, s[4:5] offset:48 sc1
	global_load_dword v9, v1, s[4:5] offset:52 sc1
	global_load_dword v10, v1, s[4:5] offset:56 sc1
	global_load_dword v11, v1, s[4:5] offset:60 sc1
	s_mov_b32 s14, 0
	s_mov_b32 s15, 1
	s_mov_b32 vcc_hi, 0
	s_waitcnt vmcnt(0)
	v_readfirstlane_b32 vcc_lo, v4
	s_nop 3
	s_add_u32 vcc_hi, vcc_hi, vcc_lo
	s_cmp_lg_u32 vcc_lo, 0
	s_addc_u32 s14, s14, 0
	s_cmp_eq_u32 s100, 0
	s_cselect_b32 s15, vcc_lo, s15
	v_readfirstlane_b32 vcc_lo, v5
	s_nop 3
	s_add_u32 vcc_hi, vcc_hi, vcc_lo
	s_cmp_lg_u32 vcc_lo, 0
	s_addc_u32 s14, s14, 0
	s_cmp_eq_u32 s100, 1
	s_cselect_b32 s15, vcc_lo, s15
	v_readfirstlane_b32 vcc_lo, v6
	s_nop 3
	s_add_u32 vcc_hi, vcc_hi, vcc_lo
	s_cmp_lg_u32 vcc_lo, 0
	s_addc_u32 s14, s14, 0
	s_cmp_eq_u32 s100, 2
	s_cselect_b32 s15, vcc_lo, s15
	v_readfirstlane_b32 vcc_lo, v7
	s_nop 3
	s_add_u32 vcc_hi, vcc_hi, vcc_lo
	s_cmp_lg_u32 vcc_lo, 0
	s_addc_u32 s14, s14, 0
	s_cmp_eq_u32 s100, 3
	s_cselect_b32 s15, vcc_lo, s15
	v_readfirstlane_b32 vcc_lo, v8
	s_nop 3
	s_add_u32 vcc_hi, vcc_hi, vcc_lo
	s_cmp_lg_u32 vcc_lo, 0
	s_addc_u32 s14, s14, 0
	s_cmp_eq_u32 s100, 4
	s_cselect_b32 s15, vcc_lo, s15
	v_readfirstlane_b32 vcc_lo, v9
	s_nop 3
	s_add_u32 vcc_hi, vcc_hi, vcc_lo
	s_cmp_lg_u32 vcc_lo, 0
	s_addc_u32 s14, s14, 0
	s_cmp_eq_u32 s100, 5
	s_cselect_b32 s15, vcc_lo, s15
	v_readfirstlane_b32 vcc_lo, v10
	s_nop 3
	s_add_u32 vcc_hi, vcc_hi, vcc_lo
	s_cmp_lg_u32 vcc_lo, 0
	s_addc_u32 s14, s14, 0
	s_cmp_eq_u32 s100, 6
	s_cselect_b32 s15, vcc_lo, s15
	v_readfirstlane_b32 vcc_lo, v11
	s_nop 3
	s_add_u32 vcc_hi, vcc_hi, vcc_lo
	s_cmp_lg_u32 vcc_lo, 0
	s_addc_u32 s14, s14, 0
	s_cmp_eq_u32 s100, 7
	s_cselect_b32 s15, vcc_lo, s15
	s_cmp_eq_u32 vcc_hi, s9
	s_cbranch_scc1 .Lxb_census_done2
	s_sleep 2
	s_add_u32 s101, s101, 1
	s_cmp_gt_u32 s101, 65536
	s_cbranch_scc0 .Lxb_census_retry
	s_branch .Lxb_census_ok
.Lxb_census_done2:
	s_mov_b32 s101, 0
.Lxb_census_ok:
	s_lshl_b32 s15, s15, 8
	s_lshl_b32 s14, s14, 24
	s_or_b32 s100, s100, s15
	s_or_b32 s100, s100, s14

; DI int TID() { int t = threadIdx.x; asm volatile("" : "+v"(t)); return t; }
; DI void grid_barrier_light(unsigned* ctr, unsigned target) {
;     ...
;   if (TID() == 0) {
;     __builtin_amdgcn_fence(__ATOMIC_RELEASE, "agent");
;     asm volatile("s_waitcnt vmcnt(0)" ::: "memory");
;     __hip_atomic_fetch_add(ctr, 1u, __ATOMIC_RELAXED, __HIP_MEMORY_SCOPE_AGENT);
;     while (__hip_atomic_load(ctr, __ATOMIC_RELAXED, __HIP_MEMORY_SCOPE_AGENT) < target) { }
;     __builtin_amdgcn_fence(__ATOMIC_ACQUIRE, "agent");
.Lxb_top_spin:
	s_cmp_lg_u32 s101, 0
	s_cbranch_scc1 .Lxb_top_done
	s_sleep 1
	global_load_dword v3, v1, s[6:7] sc1
	s_add_u32 s14, s14, 1
	s_cmp_gt_u32 s14, 65536
	s_cselect_b32 s101, 1, s101
	s_waitcnt vmcnt(0)
	v_readfirstlane_b32 s15, v3
	s_nop 3
	s_cmp_lt_u32 s15, s8
	s_cbranch_scc1 .Lxb_top_spin

; DI int TID() { int t = threadIdx.x; asm volatile("" : "+v"(t)); return t; }
; DI void grid_barrier_light(unsigned* ctr, unsigned target) {
;     ...
;   if (TID() == 0) {
;     __builtin_amdgcn_fence(__ATOMIC_RELEASE, "agent");
;     asm volatile("s_waitcnt vmcnt(0)" ::: "memory");
;     __hip_atomic_fetch_add(ctr, 1u, __ATOMIC_RELAXED, __HIP_MEMORY_SCOPE_AGENT);
;     while (__hip_atomic_load(ctr, __ATOMIC_RELAXED, __HIP_MEMORY_SCOPE_AGENT) < target) { }
;     __builtin_amdgcn_fence(__ATOMIC_ACQUIRE, "agent");
.Lxb_f_spin:
	s_cmp_lg_u32 s101, 0
	s_cbranch_scc1 .Lxb_f_done
	s_sleep 1
	global_load_dword v3, v4, s[6:7] sc1
	s_add_u32 s14, s14, 1
	s_cmp_gt_u32 s14, 65536
	s_cselect_b32 s101, 1, s101
	s_waitcnt vmcnt(0)
	v_readfirstlane_b32 s15, v3
	s_nop 3
	s_cmp_lt_u32 s15, s8
	s_cbranch_scc1 .Lxb_f_spin
